# down GEMM decode rows: all 48 operand loads of the split-K loop issued at once (one round trip instead of four), same MFMA order
# speedup vs baseline: 1.0130x; 1.0009x over previous
.LBB0_1222:
	s_lshl_b32 s4, s24, 1
	s_and_b32 s6, s4, 0xe0000
	s_and_b32 s4, s3, 0xffffffe0
	s_ashr_i32 s5, s4, 31
	v_readlane_b32 s36, v252, 0
	s_lshl_b64 s[4:5], s[4:5], 13
	v_readlane_b32 s42, v252, 6
	v_readlane_b32 s43, v252, 7
	v_lshl_add_u64 v[22:23], v[12:13], 0, s[6:7]
	v_lshl_add_u64 v[24:25], v[14:15], 0, s[4:5]
	v_lshl_add_u64 v[26:27], v[16:17], 0, s[4:5]
	s_mov_b32 s6, -4
	s_mov_b64 s[4:5], s[42:43]
	v_mov_b32_e32 v0, 0
	v_mov_b32_e32 v1, v11
	v_mov_b32_e32 v2, v11
	v_mov_b32_e32 v3, v11
	v_mov_b32_e32 v4, 0
	v_mov_b32_e32 v5, v11
	v_mov_b32_e32 v6, v11
	v_mov_b32_e32 v7, v11
	v_readlane_b32 s37, v252, 1
	v_readlane_b32 s38, v252, 2
	v_readlane_b32 s39, v252, 3
	v_readlane_b32 s40, v252, 4
	v_readlane_b32 s41, v252, 5
	v_lshl_add_u64 v[246:247], s[4:5], 0, v[22:23]
	v_lshl_add_u64 v[248:249], s[4:5], 0, v[24:25]
	v_lshl_add_u64 v[250:251], s[4:5], 0, v[26:27]
	v_add_co_u32_e32 v246, vcc, 0xe1a0000, v246
	s_nop 1
	v_addc_co_u32_e32 v247, vcc, 0, v247, vcc
	v_add_co_u32_e32 v248, vcc, 0x1920000, v248
	s_nop 1
	v_addc_co_u32_e32 v249, vcc, 0, v249, vcc
	v_add_co_u32_e32 v250, vcc, 0x1920000, v250
	s_nop 1
	v_addc_co_u32_e32 v251, vcc, 0, v251, vcc
	global_load_dwordx4 v[32:35], v[246:247], off sc1
	global_load_dwordx4 v[36:39], v[248:249], off
	global_load_dwordx4 v[40:43], v[250:251], off
	global_load_dwordx4 v[44:47], v[246:247], off offset:64 sc1
	global_load_dwordx4 v[48:51], v[248:249], off offset:64
	global_load_dwordx4 v[52:55], v[250:251], off offset:64
	global_load_dwordx4 v[56:59], v[246:247], off offset:128 sc1
	global_load_dwordx4 v[60:63], v[248:249], off offset:128
	global_load_dwordx4 v[64:67], v[250:251], off offset:128
	global_load_dwordx4 v[68:71], v[246:247], off offset:192 sc1
	global_load_dwordx4 v[72:75], v[248:249], off offset:192
	global_load_dwordx4 v[76:79], v[250:251], off offset:192
	global_load_dwordx4 v[80:83], v[246:247], off offset:256 sc1
	global_load_dwordx4 v[84:87], v[248:249], off offset:256
	global_load_dwordx4 v[88:91], v[250:251], off offset:256
	global_load_dwordx4 v[92:95], v[246:247], off offset:320 sc1
	global_load_dwordx4 v[96:99], v[248:249], off offset:320
	global_load_dwordx4 v[100:103], v[250:251], off offset:320
	global_load_dwordx4 v[104:107], v[246:247], off offset:384 sc1
	global_load_dwordx4 v[108:111], v[248:249], off offset:384
	global_load_dwordx4 v[112:115], v[250:251], off offset:384
	global_load_dwordx4 v[116:119], v[246:247], off offset:448 sc1
	global_load_dwordx4 v[120:123], v[248:249], off offset:448
	global_load_dwordx4 v[124:127], v[250:251], off offset:448
	global_load_dwordx4 v[128:131], v[246:247], off offset:512 sc1
	global_load_dwordx4 v[132:135], v[248:249], off offset:512
	global_load_dwordx4 v[136:139], v[250:251], off offset:512
	global_load_dwordx4 v[140:143], v[246:247], off offset:576 sc1
	global_load_dwordx4 v[144:147], v[248:249], off offset:576
	global_load_dwordx4 v[148:151], v[250:251], off offset:576
	global_load_dwordx4 v[152:155], v[246:247], off offset:640 sc1
	global_load_dwordx4 v[156:159], v[248:249], off offset:640
	global_load_dwordx4 v[160:163], v[250:251], off offset:640
	global_load_dwordx4 v[164:167], v[246:247], off offset:704 sc1
	global_load_dwordx4 v[168:171], v[248:249], off offset:704
	global_load_dwordx4 v[172:175], v[250:251], off offset:704
	global_load_dwordx4 v[180:183], v[246:247], off offset:768 sc1
	global_load_dwordx4 v[184:187], v[248:249], off offset:768
	global_load_dwordx4 v[188:191], v[250:251], off offset:768
	global_load_dwordx4 v[192:195], v[246:247], off offset:832 sc1
	global_load_dwordx4 v[196:199], v[248:249], off offset:832
	global_load_dwordx4 v[200:203], v[250:251], off offset:832
	global_load_dwordx4 v[204:207], v[246:247], off offset:896 sc1
	global_load_dwordx4 v[208:211], v[248:249], off offset:896
	global_load_dwordx4 v[212:215], v[250:251], off offset:896
	global_load_dwordx4 v[216:219], v[246:247], off offset:960 sc1
	global_load_dwordx4 v[220:223], v[248:249], off offset:960
	global_load_dwordx4 v[224:227], v[250:251], off offset:960
	s_waitcnt vmcnt(45)
	v_mfma_f32_16x16x32_bf16 v[0:3], v[36:39], v[32:35], v[0:3]
	v_mfma_f32_16x16x32_bf16 v[4:7], v[40:43], v[32:35], v[4:7]
	s_waitcnt vmcnt(42)
	v_mfma_f32_16x16x32_bf16 v[0:3], v[48:51], v[44:47], v[0:3]
	v_mfma_f32_16x16x32_bf16 v[4:7], v[52:55], v[44:47], v[4:7]
	s_waitcnt vmcnt(39)
	v_mfma_f32_16x16x32_bf16 v[0:3], v[60:63], v[56:59], v[0:3]
	v_mfma_f32_16x16x32_bf16 v[4:7], v[64:67], v[56:59], v[4:7]
	s_waitcnt vmcnt(36)
	v_mfma_f32_16x16x32_bf16 v[0:3], v[72:75], v[68:71], v[0:3]
	v_mfma_f32_16x16x32_bf16 v[4:7], v[76:79], v[68:71], v[4:7]
	s_waitcnt vmcnt(33)
	v_mfma_f32_16x16x32_bf16 v[0:3], v[84:87], v[80:83], v[0:3]
	v_mfma_f32_16x16x32_bf16 v[4:7], v[88:91], v[80:83], v[4:7]
	s_waitcnt vmcnt(30)
	v_mfma_f32_16x16x32_bf16 v[0:3], v[96:99], v[92:95], v[0:3]
	v_mfma_f32_16x16x32_bf16 v[4:7], v[100:103], v[92:95], v[4:7]
	s_waitcnt vmcnt(27)
	v_mfma_f32_16x16x32_bf16 v[0:3], v[108:111], v[104:107], v[0:3]
	v_mfma_f32_16x16x32_bf16 v[4:7], v[112:115], v[104:107], v[4:7]
	s_waitcnt vmcnt(24)
	v_mfma_f32_16x16x32_bf16 v[0:3], v[120:123], v[116:119], v[0:3]
	v_mfma_f32_16x16x32_bf16 v[4:7], v[124:127], v[116:119], v[4:7]
	s_waitcnt vmcnt(21)
	v_mfma_f32_16x16x32_bf16 v[0:3], v[132:135], v[128:131], v[0:3]
	v_mfma_f32_16x16x32_bf16 v[4:7], v[136:139], v[128:131], v[4:7]
	s_waitcnt vmcnt(18)
	v_mfma_f32_16x16x32_bf16 v[0:3], v[144:147], v[140:143], v[0:3]
	v_mfma_f32_16x16x32_bf16 v[4:7], v[148:151], v[140:143], v[4:7]
	s_waitcnt vmcnt(15)
	v_mfma_f32_16x16x32_bf16 v[0:3], v[156:159], v[152:155], v[0:3]
	v_mfma_f32_16x16x32_bf16 v[4:7], v[160:163], v[152:155], v[4:7]
	s_waitcnt vmcnt(12)
	v_mfma_f32_16x16x32_bf16 v[0:3], v[168:171], v[164:167], v[0:3]
	v_mfma_f32_16x16x32_bf16 v[4:7], v[172:175], v[164:167], v[4:7]
	s_waitcnt vmcnt(9)
	v_mfma_f32_16x16x32_bf16 v[0:3], v[184:187], v[180:183], v[0:3]
	v_mfma_f32_16x16x32_bf16 v[4:7], v[188:191], v[180:183], v[4:7]
	s_waitcnt vmcnt(6)
	v_mfma_f32_16x16x32_bf16 v[0:3], v[196:199], v[192:195], v[0:3]
	v_mfma_f32_16x16x32_bf16 v[4:7], v[200:203], v[192:195], v[4:7]
	s_waitcnt vmcnt(3)
	v_mfma_f32_16x16x32_bf16 v[0:3], v[208:211], v[204:207], v[0:3]
	v_mfma_f32_16x16x32_bf16 v[4:7], v[212:215], v[204:207], v[4:7]
	s_waitcnt vmcnt(0)
	v_mfma_f32_16x16x32_bf16 v[0:3], v[220:223], v[216:219], v[0:3]
	v_mfma_f32_16x16x32_bf16 v[4:7], v[224:227], v[216:219], v[4:7]
	s_nop 1
	v_add_u32_e32 v19, s22, v9
	s_andn2_b64 vcc, exec, s[10:11]
	s_nop 2
	ds_write_b128 v19, v[0:3]
	s_nop 0
	ds_write_b128 v19, v[4:7] offset:1024
	s_waitcnt lgkmcnt(0)
	s_barrier
	s_cbranch_vccnz .LBB0_1221
	v_add_u32_e32 v19, s23, v9
	ds_read_b128 v[0:3], v19 offset:2048
	ds_read_b128 v[4:7], v19
	ds_read_b128 v[22:25], v19 offset:1024
	ds_read_b128 v[32:35], v19 offset:3072
	ds_read_b128 v[36:39], v19 offset:4096
	v_readlane_b32 s36, v252, 0
	s_waitcnt lgkmcnt(3)
	v_pk_add_f32 v[6:7], v[6:7], v[2:3]
	v_pk_add_f32 v[26:27], v[4:5], v[0:1]
	ds_read_b128 v[0:3], v19 offset:5120
	s_waitcnt lgkmcnt(2)
	v_pk_add_f32 v[24:25], v[24:25], v[34:35]
	s_waitcnt lgkmcnt(1)
	v_pk_add_f32 v[34:35], v[6:7], v[38:39]
	ds_read_b128 v[4:7], v19 offset:6144
	v_pk_add_f32 v[32:33], v[22:23], v[32:33]
	v_pk_add_f32 v[26:27], v[26:27], v[36:37]
	s_waitcnt lgkmcnt(1)
	v_pk_add_f32 v[36:37], v[24:25], v[2:3]
	ds_read_b128 v[22:25], v19 offset:7168
	v_pk_add_f32 v[32:33], v[32:33], v[0:1]
	s_waitcnt lgkmcnt(1)
	v_pk_add_f32 v[34:35], v[34:35], v[6:7]
	ds_read_b128 v[0:3], v19 offset:8192
	v_pk_add_f32 v[26:27], v[26:27], v[4:5]
	ds_read_b128 v[4:7], v19 offset:9216
	s_waitcnt lgkmcnt(2)
	v_pk_add_f32 v[36:37], v[36:37], v[24:25]
	v_pk_add_f32 v[32:33], v[32:33], v[22:23]
	ds_read_b128 v[22:25], v19 offset:10240
	s_waitcnt lgkmcnt(2)
	v_pk_add_f32 v[34:35], v[34:35], v[2:3]
	v_pk_add_f32 v[26:27], v[26:27], v[0:1]
	s_waitcnt lgkmcnt(1)
	v_pk_add_f32 v[36:37], v[36:37], v[6:7]
	ds_read_b128 v[0:3], v19 offset:11264
	v_pk_add_f32 v[32:33], v[32:33], v[4:5]
	ds_read_b128 v[4:7], v19 offset:12288
	s_waitcnt lgkmcnt(2)
	v_pk_add_f32 v[24:25], v[34:35], v[24:25]
	v_pk_add_f32 v[26:27], v[26:27], v[22:23]
	s_waitcnt lgkmcnt(1)
	v_pk_add_f32 v[36:37], v[36:37], v[2:3]
	v_pk_add_f32 v[38:39], v[32:33], v[0:1]
	ds_read_b128 v[0:3], v19 offset:13312
	s_waitcnt lgkmcnt(1)
	v_pk_add_f32 v[6:7], v[24:25], v[6:7]
	ds_read_b128 v[22:25], v19 offset:14336
	ds_read_b128 v[32:35], v19 offset:15360
	v_pk_add_f32 v[26:27], v[26:27], v[4:5]
	s_waitcnt lgkmcnt(2)
	v_pk_add_f32 v[2:3], v[36:37], v[2:3]
	v_pk_add_f32 v[36:37], v[38:39], v[0:1]
	s_waitcnt lgkmcnt(1)
	v_pk_add_f32 v[4:5], v[6:7], v[24:25]
	v_pk_add_f32 v[6:7], v[26:27], v[22:23]
	v_mul_f32_e32 v20, v5, v5
	v_mul_f32_e32 v19, v7, v7
	s_waitcnt lgkmcnt(0)
	v_pk_add_f32 v[0:1], v[2:3], v[34:35]
	v_pk_add_f32 v[2:3], v[36:37], v[32:33]
	v_fmac_f32_e32 v19, v6, v6
	v_fmac_f32_e32 v20, v4, v4
	v_add_f32_e32 v19, v19, v20
	v_mul_f32_e32 v20, v3, v3
	v_mul_f32_e32 v22, v1, v1
	v_fmac_f32_e32 v20, v2, v2
	v_fmac_f32_e32 v22, v0, v0
	v_add_f32_e32 v20, v20, v22
	v_and_b32_e32 v22, 64, v177
	v_add_f32_e32 v19, v19, v20
	v_xor_b32_e32 v20, 16, v177
	v_add_u32_e32 v22, 64, v22
	v_cmp_lt_i32_e32 vcc, v20, v22
	s_add_i32 s4, s72, s2
	v_readlane_b32 s40, v252, 4
	v_cndmask_b32_e32 v20, v177, v20, vcc
	v_lshlrev_b32_e32 v26, 2, v20
	ds_bpermute_b32 v20, v26, v19
	v_readlane_b32 s41, v252, 5
	s_and_b32 s6, s4, 7
	v_readlane_b32 s42, v252, 6
	v_readlane_b32 s43, v252, 7
	s_waitcnt lgkmcnt(0)
	v_add_f32_e32 v19, v19, v20
	v_xor_b32_e32 v20, 32, v177
	v_cmp_lt_i32_e32 vcc, v20, v22
	s_mov_b64 s[16:17], s[40:41]
	s_ashr_i32 s4, s4, 3
	v_cndmask_b32_e32 v20, v177, v20, vcc
	v_lshlrev_b32_e32 v27, 2, v20
	s_lshl_b32 s5, s6, 12
	ds_bpermute_b32 v20, v27, v19
	s_mov_b64 s[18:19], s[42:43]
	s_add_u32 s5, s18, s5
	s_addc_u32 s15, s19, 0
	s_add_u32 s14, s5, 0xe4b0000
	s_addc_u32 s15, s15, 0
	v_readlane_b32 s37, v252, 1
	v_readlane_b32 s38, v252, 2
	v_readlane_b32 s39, v252, 3
	s_and_saveexec_b64 s[16:17], s[0:1]
	s_cbranch_execz .LBB0_1227
	s_waitcnt lgkmcnt(0)
	v_add_f32_e32 v20, v19, v20
	v_mov_b32_e32 v19, v11
	v_lshl_add_u64 v[22:23], s[14:15], 0, v[18:19]
	s_ashr_i32 s5, s4, 31
	v_lshl_add_u64 v[22:23], s[4:5], 3, v[22:23]
	global_store_dwordx2 v[22:23], v[20:21], off sc1
